# v41 + neighbourhood-attention bias-lookup waits paired (16 counted lgkmcnt per step instead of 32)
# speedup vs baseline: 1.0022x; 1.0000x over previous
; __device__ __forceinline__ int crow(int r, int hi) { return (r & 3) + 8 * (r >> 2) + 4 * hi; }
;   p0 = f32x16{}; p1 = f32x16{};
; #pragma unroll
;   for (int d0 = DLO; d0 < DHI; ++d0) { int cb = (d0 * 16 + hi * 8) * 2;
;     bf16x8 b0 = *reinterpret_cast<const bf16x8*>((const char*)Ks + KSWZ(r32, cb));
;     bf16x8 b1 = *reinterpret_cast<const bf16x8*>((const char*)Ks + KSWZ(32 + r32, cb));
;     p0 = __builtin_amdgcn_mfma_f32_32x32x16_bf16(b0, qr[d0], p0, 0, 0, 0);
;     p1 = __builtin_amdgcn_mfma_f32_32x32x16_bf16(b1, qr[d0], p1, 0, 0, 0); }
; }
; __device__ __forceinline__ void na_item(const int g_wave, int b, int r, int hp, const bf16* __restrict__ proj, const float* __restrict__ rpb, bf16* __restrict__ cat, char* lds) {
;     ...
;     const float* bp = btab + (hl * 15 + (kr - r + 7)) * 31;
;     float tmax = NEG;
; #pragma unroll
;     for (int q = 0; q < 16; ++q) {
;       const int j0 = crow(q, hi), j1 = 32 + j0;
;       { const bool ok = (j0 >= cs) && (j0 < cs + 16); int dc = j0 - c + 15; dc = dc < 0 ? 0 : (dc > 30 ? 30 : dc);
;         const float bv = bp[dc]; p0[q] = ok ? fmaf(p0[q], C, bv) : NEG; tmax = fmaxf(tmax, p0[q]); }
;       { const bool ok = (j1 >= cs) && (j1 < cs + 16); int dc = j1 - c + 15; dc = dc < 0 ? 0 : (dc > 30 ? 30 : dc);
;         const float bv = bp[dc]; p1[q] = ok ? fmaf(p1[q], C, bv) : NEG; tmax = fmaxf(tmax, p1[q]); }
;     }
.Lna_active:
	s_barrier
	ds_read_b128 v[230:233], v218
	v_add_u32_e32 v0, v139, v137
	ds_read_b128 v[234:237], v0 offset:8192
	ds_read_b128 v[238:241], v219
	v_add_u32_e32 v0, v139, v141
	ds_read_b128 v[242:245], v0 offset:8192
	ds_read_b128 v[246:249], v220
	v_add_u32_e32 v0, v139, v143
	ds_read_b128 v[186:189], v0 offset:8192
	s_waitcnt lgkmcnt(4)
	v_mfma_f32_32x32x16_bf16 v[82:97], v[230:233], v[122:125], 0
	ds_read_b128 v[230:233], v221
	v_mfma_f32_32x32x16_bf16 v[66:81], v[234:237], v[122:125], 0
	v_add_u32_e32 v0, v139, v145
	ds_read_b128 v[234:237], v0 offset:8192
	s_waitcnt lgkmcnt(4)
	v_mfma_f32_32x32x16_bf16 v[82:97], v[238:241], v[98:101], v[82:97]
	ds_read_b128 v[238:241], v222
	v_mfma_f32_32x32x16_bf16 v[66:81], v[242:245], v[98:101], v[66:81]
	v_add_u32_e32 v0, v139, v149
	ds_read_b128 v[242:245], v0 offset:8192
	s_waitcnt lgkmcnt(4)
	v_mfma_f32_32x32x16_bf16 v[82:97], v[246:249], v[102:105], v[82:97]
	ds_read_b128 v[246:249], v223
	v_mfma_f32_32x32x16_bf16 v[66:81], v[186:189], v[102:105], v[66:81]
	v_add_u32_e32 v0, v139, v151
	ds_read_b128 v[186:189], v0 offset:8192
	s_waitcnt lgkmcnt(4)
	v_mfma_f32_32x32x16_bf16 v[82:97], v[230:233], v[106:109], v[82:97]
	ds_read_b128 v[230:233], v224
	v_mfma_f32_32x32x16_bf16 v[66:81], v[234:237], v[106:109], v[66:81]
	v_add_u32_e32 v0, v139, v153
	ds_read_b128 v[234:237], v0 offset:8192
	s_waitcnt lgkmcnt(4)
	v_mfma_f32_32x32x16_bf16 v[82:97], v[238:241], v[110:113], v[82:97]
	ds_read_b128 v[238:241], v225
	v_mfma_f32_32x32x16_bf16 v[66:81], v[242:245], v[110:113], v[66:81]
	v_add_u32_e32 v0, v139, v155
	ds_read_b128 v[242:245], v0 offset:8192
	s_waitcnt lgkmcnt(4)
	v_mfma_f32_32x32x16_bf16 v[82:97], v[246:249], v[114:117], v[82:97]
	v_mfma_f32_32x32x16_bf16 v[66:81], v[186:189], v[114:117], v[66:81]
	s_waitcnt lgkmcnt(2)
	v_mfma_f32_32x32x16_bf16 v[82:97], v[230:233], v[118:121], v[82:97]
	v_mfma_f32_32x32x16_bf16 v[66:81], v[234:237], v[118:121], v[66:81]
	s_waitcnt lgkmcnt(0)
	v_mfma_f32_32x32x16_bf16 v[82:97], v[238:241], v[126:129], v[82:97]
	v_mfma_f32_32x32x16_bf16 v[66:81], v[242:245], v[126:129], v[66:81]
	v_mov_b32_e32 v244, 0xf149f2ca
	v_add_u32_e32 v230, s43, v157
	ds_read_b32 v230, v230
	v_add_u32_e32 v231, s43, v159
	ds_read_b32 v231, v231
	v_add_u32_e32 v232, s43, v161
	ds_read_b32 v232, v232
	v_add_u32_e32 v233, s43, v164
	ds_read_b32 v233, v233
	v_add_u32_e32 v234, s43, v165
	ds_read_b32 v234, v234
	v_add_u32_e32 v235, s43, v166
	ds_read_b32 v235, v235
	v_add_u32_e32 v236, s43, v167
	ds_read_b32 v236, v236
	v_add_u32_e32 v237, s43, v168
	ds_read_b32 v237, v237
	v_add_u32_e32 v238, s43, v169
	ds_read_b32 v238, v238
	v_add_u32_e32 v239, s43, v170
	ds_read_b32 v239, v239
	v_add_u32_e32 v240, s43, v171
	ds_read_b32 v240, v240
	v_add_u32_e32 v241, s43, v172
	ds_read_b32 v241, v241
	v_add_u32_e32 v242, s43, v173
	ds_read_b32 v242, v242
	v_add_u32_e32 v243, s43, v174
	ds_read_b32 v243, v243
	s_waitcnt lgkmcnt(12)
	v_fmac_f32_e32 v230, 0x3e0293ee, v82
	v_cndmask_b32_e64 v229, v244, v230, s[26:27]
	v_add_u32_e32 v230, s43, v175
	ds_read_b32 v230, v230
	v_fmac_f32_e32 v231, 0x3e0293ee, v66
	v_cndmask_b32_e64 v228, v244, v231, s[28:29]
	v_add_u32_e32 v231, s43, v176
	ds_read_b32 v231, v231
	s_waitcnt lgkmcnt(12)
	v_fmac_f32_e32 v232, 0x3e0293ee, v83
	v_cndmask_b32_e64 v82, v244, v232, s[30:31]
	v_add_u32_e32 v232, s43, v177
	ds_read_b32 v232, v232
	v_fmac_f32_e32 v233, 0x3e0293ee, v67
	v_cndmask_b32_e64 v66, v244, v233, s[82:83]
	v_add_u32_e32 v233, s43, v190
	ds_read_b32 v233, v233
	s_waitcnt lgkmcnt(12)
	v_fmac_f32_e32 v234, 0x3e0293ee, v84
	v_cndmask_b32_e64 v83, v244, v234, s[84:85]
	v_add_u32_e32 v234, s43, v191
	ds_read_b32 v234, v234
	v_fmac_f32_e32 v235, 0x3e0293ee, v68
	v_cndmask_b32_e64 v67, v244, v235, s[86:87]
	v_add_u32_e32 v235, s43, v192
	ds_read_b32 v235, v235
	s_waitcnt lgkmcnt(12)
	v_fmac_f32_e32 v236, 0x3e0293ee, v85
	v_cndmask_b32_e64 v84, v244, v236, s[88:89]
	v_add_u32_e32 v236, s43, v193
	ds_read_b32 v236, v236
	v_fmac_f32_e32 v237, 0x3e0293ee, v69
	v_cndmask_b32_e64 v68, v244, v237, s[90:91]
	v_add_u32_e32 v237, s43, v194
	ds_read_b32 v237, v237
	s_waitcnt lgkmcnt(12)
	v_fmac_f32_e32 v238, 0x3e0293ee, v86
	v_cndmask_b32_e64 v85, v244, v238, s[92:93]
	v_add_u32_e32 v238, s43, v195
	ds_read_b32 v238, v238
	v_fmac_f32_e32 v239, 0x3e0293ee, v70
	v_cndmask_b32_e64 v69, v244, v239, s[94:95]
	v_add_u32_e32 v239, s43, v196
	ds_read_b32 v239, v239
	s_waitcnt lgkmcnt(12)
	v_fmac_f32_e32 v240, 0x3e0293ee, v87
	v_cndmask_b32_e64 v86, v244, v240, s[96:97]
	v_add_u32_e32 v240, s43, v197
	ds_read_b32 v240, v240
	v_fmac_f32_e32 v241, 0x3e0293ee, v71
	v_cndmask_b32_e64 v70, v244, v241, s[60:61]
	v_add_u32_e32 v241, s43, v207
	ds_read_b32 v241, v241
	s_waitcnt lgkmcnt(12)
	v_fmac_f32_e32 v242, 0x3e0293ee, v88
	v_cndmask_b32_e64 v87, v244, v242, s[38:39]
	v_add_u32_e32 v242, s43, v208
	ds_read_b32 v242, v242
	v_fmac_f32_e32 v243, 0x3e0293ee, v72
	v_cndmask_b32_e64 v71, v244, v243, s[74:75]
	v_add_u32_e32 v243, s43, v209
	ds_read_b32 v243, v243
	s_waitcnt lgkmcnt(12)
	v_fmac_f32_e32 v230, 0x3e0293ee, v89
	v_cndmask_b32_e64 v88, v244, v230, s[36:37]
	v_add_u32_e32 v230, s43, v210
	ds_read_b32 v230, v230
	v_fmac_f32_e32 v231, 0x3e0293ee, v73
	v_cndmask_b32_e64 v72, v244, v231, s[78:79]
	v_add_u32_e32 v231, s43, v211
	ds_read_b32 v231, v231
	s_waitcnt lgkmcnt(12)
	v_fmac_f32_e32 v232, 0x3e0293ee, v90
	v_cndmask_b32_e64 v89, v244, v232, s[4:5]
	v_add_u32_e32 v232, s43, v212
	ds_read_b32 v232, v232
	v_fmac_f32_e32 v233, 0x3e0293ee, v74
	v_cndmask_b32_e64 v73, v244, v233, s[14:15]
	v_add_u32_e32 v233, s43, v213
	ds_read_b32 v233, v233
	s_waitcnt lgkmcnt(12)
; __device__ __forceinline__ int crow(int r, int hi) { return (r & 3) + 8 * (r >> 2) + 4 * hi; }
; __device__ __forceinline__ void na_item(const int g_wave, int b, int r, int hp, const bf16* __restrict__ proj, const float* __restrict__ rpb, bf16* __restrict__ cat, char* lds) {
;     ...
;     const float* bp = btab + (hl * 15 + (kr - r + 7)) * 31;
;     float tmax = NEG;
; #pragma unroll
;     for (int q = 0; q < 16; ++q) {
;       const int j0 = crow(q, hi), j1 = 32 + j0;
;       { const bool ok = (j0 >= cs) && (j0 < cs + 16); int dc = j0 - c + 15; dc = dc < 0 ? 0 : (dc > 30 ? 30 : dc);
;         const float bv = bp[dc]; p0[q] = ok ? fmaf(p0[q], C, bv) : NEG; tmax = fmaxf(tmax, p0[q]); }
;       { const bool ok = (j1 >= cs) && (j1 < cs + 16); int dc = j1 - c + 15; dc = dc < 0 ? 0 : (dc > 30 ? 30 : dc);
;         const float bv = bp[dc]; p1[q] = ok ? fmaf(p1[q], C, bv) : NEG; tmax = fmaxf(tmax, p1[q]); }
;     }
;     { auto rr = __builtin_amdgcn_permlane32_swap(__float_as_uint(tmax), __float_as_uint(tmax), false, false);
;       tmax = fmaxf(__uint_as_float(rr[0]), __uint_as_float(rr[1])); }
;     const float mn = fmaxf(m_reg, tmax); const float alpha = __builtin_amdgcn_exp2f(m_reg - mn); m_reg = mn;
;     float ps = 0.f;
; #pragma unroll
;     for (int q = 0; q < 16; ++q) { p0[q] = __builtin_amdgcn_exp2f(p0[q] - mn); p1[q] = __builtin_amdgcn_exp2f(p1[q] - mn); ps += p0[q] + p1[q]; }
;     { auto rr = __builtin_amdgcn_permlane32_swap(__float_as_uint(ps), __float_as_uint(ps), false, false);
;       ps = __uint_as_float(rr[0]) + __uint_as_float(rr[1]); }
;     l_reg = l_reg * alpha + ps;
;     bf16x8 pa0, pa1, pa2, pa3;
;     PK4(p0, 0, pa0); PK4(p0, 8, pa1); PK4(p1, 0, pa2); PK4(p1, 8, pa3);
;     if (hi == 0) al_l[r32] = alpha; asm volatile("s_waitcnt lgkmcnt(0)" ::: "memory");
	v_fmac_f32_e32 v234, 0x3e0293ee, v91
	v_cndmask_b32_e64 v90, v244, v234, s[70:71]
	v_fmac_f32_e32 v235, 0x3e0293ee, v75
	v_cndmask_b32_e64 v74, v244, v235, s[76:77]
	s_waitcnt lgkmcnt(10)
	v_fmac_f32_e32 v236, 0x3e0293ee, v92
	v_cndmask_b32_e64 v91, v244, v236, s[12:13]
	v_fmac_f32_e32 v237, 0x3e0293ee, v76
	v_cndmask_b32_e64 v75, v244, v237, s[48:49]
	s_waitcnt lgkmcnt(8)
	v_fmac_f32_e32 v238, 0x3e0293ee, v93
	v_cndmask_b32_e64 v92, v244, v238, s[46:47]
	v_fmac_f32_e32 v239, 0x3e0293ee, v77
	v_cndmask_b32_e64 v76, v244, v239, s[2:3]
	s_waitcnt lgkmcnt(6)
	v_fmac_f32_e32 v240, 0x3e0293ee, v94
	v_cndmask_b32_e64 v93, v244, v240, s[50:51]
	v_fmac_f32_e32 v241, 0x3e0293ee, v78
	v_cndmask_b32_e64 v77, v244, v241, s[56:57]
	s_waitcnt lgkmcnt(4)
	v_fmac_f32_e32 v242, 0x3e0293ee, v95
	v_cndmask_b32_e64 v94, v244, v242, s[58:59]
	v_fmac_f32_e32 v243, 0x3e0293ee, v79
	v_cndmask_b32_e64 v78, v244, v243, s[44:45]
	s_waitcnt lgkmcnt(2)
	v_fmac_f32_e32 v230, 0x3e0293ee, v96
	v_cndmask_b32_e64 v95, v244, v230, s[80:81]
	v_fmac_f32_e32 v231, 0x3e0293ee, v80
	v_cndmask_b32_e64 v79, v244, v231, s[34:35]
	s_waitcnt lgkmcnt(0)
	v_fmac_f32_e32 v232, 0x3e0293ee, v97
	v_cndmask_b32_e64 v96, v244, v232, s[72:73]
	v_fmac_f32_e32 v233, 0x3e0293ee, v81
	v_cndmask_b32_e64 v80, v244, v233, s[8:9]
	s_mov_b32 s33, 0xf149f2ca
	v_max3_f32 v0, v229, s33, v228
	v_max3_f32 v0, v0, v82, v66
	v_max3_f32 v0, v0, v83, v67
	v_max3_f32 v0, v0, v84, v68
	v_max3_f32 v0, v0, v85, v69
	v_max3_f32 v0, v0, v86, v70
	v_max3_f32 v0, v0, v87, v71
	v_max3_f32 v0, v0, v88, v72
	v_max3_f32 v0, v0, v89, v73
	v_max3_f32 v0, v0, v90, v74
	v_max3_f32 v0, v0, v91, v75
	v_max3_f32 v0, v0, v92, v76
	v_max3_f32 v0, v0, v93, v77
	v_max3_f32 v0, v0, v94, v78
	v_max3_f32 v0, v0, v95, v79
	v_max3_f32 v0, v0, v96, v80
	v_mov_b32_e32 v81, v0
	s_nop 1
	v_permlane32_swap_b32_e32 v0, v81
	v_max3_f32 v0, v227, v0, v81
	v_sub_f32_e32 v81, v229, v0
	v_sub_f32_e32 v97, v228, v0
	v_exp_f32_e32 v81, v81
	v_exp_f32_e32 v97, v97
	v_sub_f32_e32 v82, v82, v0
	v_sub_f32_e32 v66, v66, v0
	v_exp_f32_e32 v186, v82
	v_exp_f32_e32 v187, v66
	v_sub_f32_e32 v83, v83, v0
	v_sub_f32_e32 v67, v67, v0
	v_sub_f32_e32 v66, v227, v0
	v_exp_f32_e32 v189, v83
	v_exp_f32_e32 v227, v67
	v_sub_f32_e32 v67, v84, v0
	v_sub_f32_e32 v68, v68, v0
	v_exp_f32_e32 v67, v67
	v_exp_f32_e32 v228, v68
	v_add_f32_e32 v82, v81, v97
	v_add_f32_e32 v82, 0, v82
	v_add_f32_e32 v188, v186, v187
	v_add_f32_e32 v68, v188, v82
	v_add_f32_e32 v82, v189, v227
	v_sub_f32_e32 v83, v85, v0
	v_sub_f32_e32 v69, v69, v0
	v_add_f32_e32 v68, v82, v68
	v_add_f32_e32 v82, v67, v228
	v_exp_f32_e32 v85, v83
	v_exp_f32_e32 v188, v69
	v_sub_f32_e32 v69, v86, v0
	v_sub_f32_e32 v70, v70, v0
	v_exp_f32_e32 v69, v69
	v_exp_f32_e32 v86, v70
	v_add_f32_e32 v68, v82, v68
	v_sub_f32_e32 v82, v87, v0
	v_sub_f32_e32 v71, v71, v0
	v_exp_f32_e32 v87, v82
	v_exp_f32_e32 v229, v71
	v_sub_f32_e32 v71, v88, v0
	v_sub_f32_e32 v72, v72, v0
	v_exp_f32_e32 v71, v71
	v_exp_f32_e32 v88, v72
	v_sub_f32_e32 v72, v89, v0
	v_sub_f32_e32 v73, v73, v0
	v_add_f32_e32 v70, v85, v188
	v_exp_f32_e32 v72, v72
	v_exp_f32_e32 v89, v73
	v_sub_f32_e32 v73, v90, v0
	v_sub_f32_e32 v74, v74, v0
	v_add_f32_e32 v68, v70, v68
	v_add_f32_e32 v70, v69, v86
	v_exp_f32_e32 v73, v73
	v_exp_f32_e32 v90, v74
	v_sub_f32_e32 v74, v91, v0
	v_sub_f32_e32 v75, v75, v0
	v_add_f32_e32 v68, v70, v68
	v_add_f32_e32 v70, v87, v229
	v_exp_f32_e32 v74, v74
	v_exp_f32_e32 v91, v75
	v_sub_f32_e32 v75, v92, v0
	v_sub_f32_e32 v76, v76, v0
	v_add_f32_e32 v68, v70, v68
	v_add_f32_e32 v70, v71, v88
	v_exp_f32_e32 v75, v75
	v_exp_f32_e32 v92, v76
	v_sub_f32_e32 v76, v93, v0
	v_sub_f32_e32 v77, v77, v0
	v_add_f32_e32 v68, v70, v68
	v_add_f32_e32 v70, v72, v89
	v_exp_f32_e32 v76, v76
	v_exp_f32_e32 v93, v77
	v_sub_f32_e32 v77, v94, v0
	v_sub_f32_e32 v78, v78, v0
	v_add_f32_e32 v68, v70, v68
	v_add_f32_e32 v70, v73, v90
	v_exp_f32_e32 v77, v77
	v_exp_f32_e32 v94, v78
	v_sub_f32_e32 v78, v95, v0
	v_sub_f32_e32 v79, v79, v0
	v_add_f32_e32 v68, v70, v68
	v_add_f32_e32 v70, v74, v91
	v_exp_f32_e32 v78, v78
	v_exp_f32_e32 v95, v79
	v_sub_f32_e32 v79, v96, v0
	v_sub_f32_e32 v80, v80, v0
	v_add_f32_e32 v68, v70, v68
	v_add_f32_e32 v70, v75, v92
	v_exp_f32_e32 v79, v79
	v_exp_f32_e32 v96, v80
	v_add_f32_e32 v68, v70, v68
	v_add_f32_e32 v70, v76, v93
	v_add_f32_e32 v68, v70, v68
	v_add_f32_e32 v70, v77, v94
	v_add_f32_e32 v68, v70, v68
	v_add_f32_e32 v70, v78, v95
	v_add_f32_e32 v68, v70, v68
	v_add_f32_e32 v70, v79, v96
	v_exp_f32_e32 v82, v66
	v_add_f32_e32 v83, v70, v68
	v_mov_b32_e32 v84, v83
	v_cvt_pk_bf16_f32 v66, v81, v186
	v_cvt_pk_bf16_f32 v67, v189, v67
	v_cvt_pk_bf16_f32 v68, v85, v69
	v_cvt_pk_bf16_f32 v69, v87, v71
	v_cvt_pk_bf16_f32 v70, v72, v73
	v_cvt_pk_bf16_f32 v71, v74, v75
	v_cvt_pk_bf16_f32 v72, v76, v77
	v_cvt_pk_bf16_f32 v73, v78, v79
	v_cvt_pk_bf16_f32 v74, v97, v187
	v_cvt_pk_bf16_f32 v75, v227, v228
	v_cvt_pk_bf16_f32 v76, v188, v86
	v_cvt_pk_bf16_f32 v77, v229, v88
	v_cvt_pk_bf16_f32 v78, v89, v90
	v_cvt_pk_bf16_f32 v79, v91, v92
	v_cvt_pk_bf16_f32 v80, v93, v94
	v_cvt_pk_bf16_f32 v81, v95, v96
	s_nop 1
	v_permlane32_swap_b32_e32 v83, v84
	v_permlane32_swap_b32_e32 v66, v68
	v_permlane32_swap_b32_e32 v67, v69
	v_permlane32_swap_b32_e32 v70, v72
	v_permlane32_swap_b32_e32 v71, v73
	v_permlane32_swap_b32_e32 v74, v76
	v_permlane32_swap_b32_e32 v75, v77
	v_permlane32_swap_b32_e32 v78, v80
	v_permlane32_swap_b32_e32 v79, v81
	s_and_saveexec_b64 s[68:69], s[6:7]
	ds_write_b32 v147, v82 offset:128
	s_or_b64 exec, exec, s[68:69]
	v_add_f32_e32 v186, v83, v84
	s_waitcnt lgkmcnt(0)
; #define SBAR() __builtin_amdgcn_sched_barrier(0)
; __device__ __forceinline__ int crow(int r, int hi) { return (r & 3) + 8 * (r >> 2) + 4 * hi; }
; template <int D0> __device__ __forceinline__ void pv_one(f32x16& od, int vb, bf16x8 pa0, bf16x8 pa1, bf16x8 pa2, bf16x8 pa3) {
;   const s16x4 l0 = tr_read<v_rd_off(D0, 0, 0)>(vb), h0 = tr_read<v_rd_off(D0, 0, 1)>(vb), l1 = tr_read<v_rd_off(D0, 1, 0)>(vb), h1 = tr_read<v_rd_off(D0, 1, 1)>(vb);
;   const s16x4 l2 = tr_read<v_rd_off(D0, 2, 0)>(vb), h2 = tr_read<v_rd_off(D0, 2, 1)>(vb), l3 = tr_read<v_rd_off(D0, 3, 0)>(vb), h3 = tr_read<v_rd_off(D0, 3, 1)>(vb);
;   asm volatile("s_waitcnt lgkmcnt(0)" ::: "memory"); SBAR();
;     ...
;   od = __builtin_amdgcn_mfma_f32_32x32x16_bf16(pa0, PK(l0, h0), od, 0, 0, 0);
;   od = __builtin_amdgcn_mfma_f32_32x32x16_bf16(pa1, PK(l1, h1), od, 0, 0, 0);
;   od = __builtin_amdgcn_mfma_f32_32x32x16_bf16(pa2, PK(l2, h2), od, 0, 0, 0);
;   od = __builtin_amdgcn_mfma_f32_32x32x16_bf16(pa3, PK(l3, h3), od, 0, 0, 0);
;     ...
; }
; __device__ __forceinline__ void na_item(const int g_wave, int b, int r, int hp, const bf16* __restrict__ proj, const float* __restrict__ rpb, bf16* __restrict__ cat, char* lds) {
;     ...
;     if (hi == 0) al_l[r32] = alpha; asm volatile("s_waitcnt lgkmcnt(0)" ::: "memory");
; #pragma unroll
;     for (int d = 0; d < 4; ++d)
; #pragma unroll
;       for (int q = 0; q < 16; ++q) o[d][q] *= al_l[crow(q, hi)];
;     pv_d0(o, vb, pa0, pa1, pa2, pa3);
	v_add_u32_e32 v94, s42, v135
	v_fmac_f32_e32 v186, v226, v82
	ds_read_b128 v[82:85], v94 offset:128
	ds_read_b128 v[86:89], v94 offset:160
	ds_read_b128 v[90:93], v94 offset:192
	ds_read_b128 v[94:97], v94 offset:224
	s_waitcnt lgkmcnt(3)
	v_pk_mul_f32 v[50:51], v[50:51], v[82:83]
	v_pk_mul_f32 v[34:35], v[34:35], v[82:83]
	v_pk_mul_f32 v[18:19], v[18:19], v[82:83]
	v_pk_mul_f32 v[2:3], v[2:3], v[82:83]
	ds_read_b64_tr_b16 v[82:83], v133 offset:0
	v_pk_mul_f32 v[52:53], v[52:53], v[84:85]
	v_pk_mul_f32 v[36:37], v[36:37], v[84:85]
	v_pk_mul_f32 v[20:21], v[20:21], v[84:85]
	v_pk_mul_f32 v[4:5], v[4:5], v[84:85]
	ds_read_b64_tr_b16 v[84:85], v133 offset:0x800
	s_waitcnt lgkmcnt(2)
	v_pk_mul_f32 v[54:55], v[54:55], v[86:87]
	v_pk_mul_f32 v[38:39], v[38:39], v[86:87]
	v_pk_mul_f32 v[22:23], v[22:23], v[86:87]
	v_pk_mul_f32 v[6:7], v[6:7], v[86:87]
	ds_read_b64_tr_b16 v[86:87], v133 offset:0x1000
	v_pk_mul_f32 v[56:57], v[56:57], v[88:89]
	v_pk_mul_f32 v[40:41], v[40:41], v[88:89]
	v_pk_mul_f32 v[24:25], v[24:25], v[88:89]
	v_pk_mul_f32 v[8:9], v[8:9], v[88:89]
	ds_read_b64_tr_b16 v[88:89], v133 offset:0x1800
	s_waitcnt lgkmcnt(1)
	v_pk_mul_f32 v[58:59], v[58:59], v[90:91]
	v_pk_mul_f32 v[42:43], v[42:43], v[90:91]
	v_pk_mul_f32 v[26:27], v[26:27], v[90:91]
	v_pk_mul_f32 v[10:11], v[10:11], v[90:91]
	ds_read_b64_tr_b16 v[90:91], v133 offset:0x2000
	v_pk_mul_f32 v[60:61], v[60:61], v[92:93]
	v_pk_mul_f32 v[44:45], v[44:45], v[92:93]
	v_pk_mul_f32 v[28:29], v[28:29], v[92:93]
	v_pk_mul_f32 v[12:13], v[12:13], v[92:93]
	ds_read_b64_tr_b16 v[92:93], v133 offset:0x2800
	s_waitcnt lgkmcnt(0)
	v_pk_mul_f32 v[62:63], v[62:63], v[94:95]
	v_pk_mul_f32 v[46:47], v[46:47], v[94:95]
	v_pk_mul_f32 v[30:31], v[30:31], v[94:95]
	v_pk_mul_f32 v[14:15], v[14:15], v[94:95]
	ds_read_b64_tr_b16 v[94:95], v133 offset:0x3000
	v_pk_mul_f32 v[64:65], v[64:65], v[96:97]
	v_pk_mul_f32 v[48:49], v[48:49], v[96:97]
	v_pk_mul_f32 v[32:33], v[32:33], v[96:97]
	v_pk_mul_f32 v[16:17], v[16:17], v[96:97]
	ds_read_b64_tr_b16 v[96:97], v133 offset:0x3800
	s_waitcnt lgkmcnt(0)
	v_mfma_f32_32x32x16_bf16 v[50:65], v[66:69], v[82:85], v[50:65]
	ds_read_b64_tr_b16 v[82:83], v133 offset:0x200
	ds_read_b64_tr_b16 v[84:85], v133 offset:0xa00
	v_mfma_f32_32x32x16_bf16 v[50:65], v[70:73], v[86:89], v[50:65]
	ds_read_b64_tr_b16 v[86:87], v133 offset:0x1200
	ds_read_b64_tr_b16 v[88:89], v133 offset:0x1a00
	v_mfma_f32_32x32x16_bf16 v[50:65], v[74:77], v[90:93], v[50:65]
	ds_read_b64_tr_b16 v[90:91], v133 offset:0x2200
	ds_read_b64_tr_b16 v[92:93], v133 offset:0x2a00
	v_mfma_f32_32x32x16_bf16 v[50:65], v[78:81], v[94:97], v[50:65]
	ds_read_b64_tr_b16 v[94:95], v133 offset:0x3200
	ds_read_b64_tr_b16 v[96:97], v133 offset:0x3a00
	s_waitcnt lgkmcnt(0)
	v_mfma_f32_32x32x16_bf16 v[34:49], v[66:69], v[82:85], v[34:49]
	ds_read_b64_tr_b16 v[82:83], v133 offset:0x400
	ds_read_b64_tr_b16 v[84:85], v133 offset:0xc00
	v_mfma_f32_32x32x16_bf16 v[34:49], v[70:73], v[86:89], v[34:49]
	ds_read_b64_tr_b16 v[86:87], v133 offset:0x1400
	ds_read_b64_tr_b16 v[88:89], v133 offset:0x1c00
	v_mfma_f32_32x32x16_bf16 v[34:49], v[74:77], v[90:93], v[34:49]
	ds_read_b64_tr_b16 v[90:91], v133 offset:0x2400
	ds_read_b64_tr_b16 v[92:93], v133 offset:0x2c00
	v_mfma_f32_32x32x16_bf16 v[34:49], v[78:81], v[94:97], v[34:49]
	ds_read_b64_tr_b16 v[94:95], v133 offset:0x3400
	ds_read_b64_tr_b16 v[96:97], v133 offset:0x3c00
	s_waitcnt lgkmcnt(0)
	v_mfma_f32_32x32x16_bf16 v[18:33], v[66:69], v[82:85], v[18:33]
	ds_read_b64_tr_b16 v[82:83], v133 offset:0x600
	ds_read_b64_tr_b16 v[84:85], v133 offset:0xe00
	v_mfma_f32_32x32x16_bf16 v[18:33], v[70:73], v[86:89], v[18:33]
	ds_read_b64_tr_b16 v[86:87], v133 offset:0x1600
	ds_read_b64_tr_b16 v[88:89], v133 offset:0x1e00
	v_mfma_f32_32x32x16_bf16 v[18:33], v[74:77], v[90:93], v[18:33]
	ds_read_b64_tr_b16 v[90:91], v133 offset:0x2600
	ds_read_b64_tr_b16 v[92:93], v133 offset:0x2e00
	v_mfma_f32_32x32x16_bf16 v[18:33], v[78:81], v[94:97], v[18:33]
	ds_read_b64_tr_b16 v[94:95], v133 offset:0x3600
	ds_read_b64_tr_b16 v[96:97], v133 offset:0x3e00
	s_waitcnt lgkmcnt(0)
	v_mfma_f32_32x32x16_bf16 v[2:17], v[66:69], v[82:85], v[2:17]
	v_mov_b32_e32 v226, v186
	v_mfma_f32_32x32x16_bf16 v[2:17], v[70:73], v[86:89], v[2:17]
	v_mfma_f32_32x32x16_bf16 v[2:17], v[74:77], v[90:93], v[2:17]
	v_mfma_f32_32x32x16_bf16 v[2:17], v[78:81], v[94:97], v[2:17]
	s_addk_i32 s43, 0x7c
	s_cmpk_eq_i32 s43, 0x3e0
	v_lshl_add_u64 v[162:163], v[162:163], 0, s[54:55]
	s_cbranch_scc0 .LBB0_1145
	s_branch .LBB0_1146
